# P2 bf16 GEMM misc (rope) tile epilogue: rope-table loads of all 8 row groups issued together into dead accumulator/fragment registers, counted waits instead of 8 serialized round trips
# speedup vs baseline: 1.0030x; 1.0007x over previous
.LBB0_823:
	s_andn2_saveexec_b64 s[6:7], s[8:9]
	s_cbranch_execz .LBB0_825
	s_waitcnt lgkmcnt(0)
	v_ashrrev_i32_e32 v68, 1, v146
	v_ashrrev_i32_e32 v69, 31, v68
	v_lshlrev_b64 v[68:69], 2, v[68:69]
	v_ashrrev_i32_e32 v145, 31, v144
	v_lshl_add_u64 v[70:71], s[22:23], 0, v[68:69]
	v_lshl_add_u64 v[68:69], s[24:25], 0, v[68:69]
	v_lshlrev_b64 v[72:73], 7, v[144:145]
	v_lshl_add_u64 v[74:75], v[70:71], 0, v[72:73]
	v_lshl_add_u64 v[78:79], v[68:69], 0, v[72:73]
	global_load_dwordx4 v[74:77], v[74:75], off
	v_ashrrev_i32_e32 v147, 31, v146
	global_load_dwordx4 v[78:81], v[78:79], off
	v_lshl_add_u64 v[86:87], v[70:71], 0, v[72:73]
	v_lshl_add_u64 v[88:89], v[68:69], 0, v[72:73]
	s_mov_b64 s[98:99], 0x1000
	v_lshl_add_u64 v[90:91], v[86:87], 0, s[98:99]
	v_lshl_add_u64 v[96:97], v[88:89], 0, s[98:99]
	s_mov_b64 s[98:99], 0x4000
	v_lshl_add_u64 v[92:93], v[86:87], 0, s[98:99]
	v_lshl_add_u64 v[98:99], v[88:89], 0, s[98:99]
	s_mov_b64 s[98:99], 0x5000
	v_lshl_add_u64 v[94:95], v[86:87], 0, s[98:99]
	v_lshl_add_u64 v[100:101], v[88:89], 0, s[98:99]
	global_load_dwordx4 v[102:105], v[86:87], off offset:2048
	global_load_dwordx4 v[156:159], v[88:89], off offset:2048
	global_load_dwordx4 v[160:163], v[96:97], off
	global_load_dwordx4 v[106:109], v[90:91], off
	global_load_dwordx4 v[164:167], v[96:97], off offset:2048
	global_load_dwordx4 v[110:113], v[90:91], off offset:2048
	global_load_dwordx4 v[168:171], v[98:99], off
	global_load_dwordx4 v[114:117], v[92:93], off
	global_load_dwordx4 v[172:175], v[98:99], off offset:2048
	global_load_dwordx4 v[118:121], v[92:93], off offset:2048
	global_load_dwordx4 v[176:179], v[100:101], off
	global_load_dwordx4 v[122:125], v[94:95], off
	global_load_dwordx4 v[180:183], v[100:101], off offset:2048
	global_load_dwordx4 v[126:129], v[94:95], off offset:2048
	s_mov_b64 s[0:1], 0x1000
	s_waitcnt vmcnt(14)
	v_pk_mul_f32 v[82:83], v[62:63], v[80:81]
	v_pk_mul_f32 v[84:85], v[60:61], v[78:79]
	v_pk_fma_f32 v[82:83], v[66:67], v[76:77], v[82:83] neg_lo:[0,0,1] neg_hi:[0,0,1]
	v_pk_fma_f32 v[84:85], v[64:65], v[74:75], v[84:85] neg_lo:[0,0,1] neg_hi:[0,0,1]
	v_pk_mul_f32 v[66:67], v[66:67], v[80:81]
	v_pk_mul_f32 v[64:65], v[64:65], v[78:79]
	v_pk_fma_f32 v[66:67], v[62:63], v[76:77], v[66:67]
	v_pk_fma_f32 v[60:61], v[60:61], v[74:75], v[64:65]
	v_cvt_pk_bf16_f32 v65, v66, v67
	v_cvt_pk_bf16_f32 v64, v60, v61
	v_lshl_add_u64 v[66:67], s[28:29], 0, v[72:73]
	v_lshlrev_b64 v[60:61], 1, v[146:147]
	v_cvt_pk_bf16_f32 v62, v84, v85
	v_cvt_pk_bf16_f32 v63, v82, v83
	v_lshl_add_u64 v[66:67], v[66:67], 0, v[60:61]
	global_store_dwordx4 v[66:67], v[62:65], off
	v_lshl_add_u64 v[66:67], v[72:73], 0, s[92:93]
	v_lshl_add_u64 v[74:75], v[68:69], 0, v[66:67]
	v_lshl_add_u64 v[62:63], v[70:71], 0, v[66:67]
	s_nop 0
	s_nop 0
	s_nop 0
	s_waitcnt vmcnt(13)
	v_pk_mul_f32 v[78:79], v[54:55], v[158:159]
	v_pk_mul_f32 v[80:81], v[52:53], v[156:157]
	v_pk_fma_f32 v[78:79], v[58:59], v[104:105], v[78:79] neg_lo:[0,0,1] neg_hi:[0,0,1]
	v_pk_fma_f32 v[80:81], v[56:57], v[102:103], v[80:81] neg_lo:[0,0,1] neg_hi:[0,0,1]
	v_pk_mul_f32 v[58:59], v[58:59], v[158:159]
	v_pk_mul_f32 v[56:57], v[56:57], v[156:157]
	v_pk_fma_f32 v[58:59], v[54:55], v[104:105], v[58:59]
	v_pk_fma_f32 v[54:55], v[52:53], v[102:103], v[56:57]
	v_lshl_add_u64 v[56:57], s[28:29], 0, v[66:67]
	v_cvt_pk_bf16_f32 v52, v80, v81
	v_cvt_pk_bf16_f32 v53, v78, v79
	v_cvt_pk_bf16_f32 v54, v54, v55
	v_cvt_pk_bf16_f32 v55, v58, v59
	v_lshl_add_u64 v[56:57], v[56:57], 0, v[60:61]
	v_lshl_add_u64 v[62:63], v[72:73], 0, s[0:1]
	global_store_dwordx4 v[56:57], v[52:55], off
	v_lshl_add_u64 v[56:57], v[68:69], 0, v[62:63]
	s_nop 0
	v_lshl_add_u64 v[52:53], v[70:71], 0, v[62:63]
	s_nop 0
	s_mov_b64 s[0:1], 0x1800
	s_waitcnt vmcnt(13)
	v_pk_mul_f32 v[64:65], v[46:47], v[162:163]
	v_pk_mul_f32 v[66:67], v[44:45], v[160:161]
	s_waitcnt vmcnt(12)
	v_pk_fma_f32 v[64:65], v[50:51], v[108:109], v[64:65] neg_lo:[0,0,1] neg_hi:[0,0,1]
	v_pk_fma_f32 v[66:67], v[48:49], v[106:107], v[66:67] neg_lo:[0,0,1] neg_hi:[0,0,1]
	v_pk_mul_f32 v[50:51], v[50:51], v[162:163]
	v_pk_mul_f32 v[48:49], v[48:49], v[160:161]
	v_pk_fma_f32 v[50:51], v[46:47], v[108:109], v[50:51]
	v_pk_fma_f32 v[46:47], v[44:45], v[106:107], v[48:49]
	v_lshl_add_u64 v[48:49], s[28:29], 0, v[62:63]
	v_cvt_pk_bf16_f32 v44, v66, v67
	v_cvt_pk_bf16_f32 v45, v64, v65
	v_cvt_pk_bf16_f32 v46, v46, v47
	v_cvt_pk_bf16_f32 v47, v50, v51
	v_lshl_add_u64 v[48:49], v[48:49], 0, v[60:61]
	v_lshl_add_u64 v[52:53], v[72:73], 0, s[0:1]
	global_store_dwordx4 v[48:49], v[44:47], off
	v_lshl_add_u64 v[48:49], v[68:69], 0, v[52:53]
	s_nop 0
	v_lshl_add_u64 v[44:45], v[70:71], 0, v[52:53]
	s_nop 0
	s_mov_b64 s[0:1], 0x4000
	s_waitcnt vmcnt(12)
	v_pk_mul_f32 v[54:55], v[38:39], v[166:167]
	v_pk_mul_f32 v[56:57], v[36:37], v[164:165]
	s_waitcnt vmcnt(11)
	v_pk_fma_f32 v[54:55], v[42:43], v[112:113], v[54:55] neg_lo:[0,0,1] neg_hi:[0,0,1]
	v_pk_fma_f32 v[56:57], v[40:41], v[110:111], v[56:57] neg_lo:[0,0,1] neg_hi:[0,0,1]
	v_pk_mul_f32 v[42:43], v[42:43], v[166:167]
	v_pk_mul_f32 v[40:41], v[40:41], v[164:165]
	v_pk_fma_f32 v[42:43], v[38:39], v[112:113], v[42:43]
	v_pk_fma_f32 v[38:39], v[36:37], v[110:111], v[40:41]
	v_lshl_add_u64 v[40:41], s[28:29], 0, v[52:53]
	v_cvt_pk_bf16_f32 v36, v56, v57
	v_cvt_pk_bf16_f32 v37, v54, v55
	v_cvt_pk_bf16_f32 v38, v38, v39
	v_cvt_pk_bf16_f32 v39, v42, v43
	v_lshl_add_u64 v[40:41], v[40:41], 0, v[60:61]
	v_lshl_add_u64 v[44:45], v[72:73], 0, s[0:1]
	global_store_dwordx4 v[40:41], v[36:39], off
	v_lshl_add_u64 v[40:41], v[68:69], 0, v[44:45]
	s_nop 0
	v_lshl_add_u64 v[36:37], v[70:71], 0, v[44:45]
	s_nop 0
	s_mov_b64 s[0:1], 0x4800
	s_waitcnt vmcnt(11)
	v_pk_mul_f32 v[46:47], v[30:31], v[170:171]
	v_pk_mul_f32 v[48:49], v[28:29], v[168:169]
	s_waitcnt vmcnt(10)
	v_pk_fma_f32 v[46:47], v[34:35], v[116:117], v[46:47] neg_lo:[0,0,1] neg_hi:[0,0,1]
	v_pk_fma_f32 v[48:49], v[32:33], v[114:115], v[48:49] neg_lo:[0,0,1] neg_hi:[0,0,1]
	v_pk_mul_f32 v[34:35], v[34:35], v[170:171]
	v_pk_mul_f32 v[32:33], v[32:33], v[168:169]
	v_pk_fma_f32 v[34:35], v[30:31], v[116:117], v[34:35]
	v_pk_fma_f32 v[30:31], v[28:29], v[114:115], v[32:33]
	v_lshl_add_u64 v[32:33], s[28:29], 0, v[44:45]
	v_cvt_pk_bf16_f32 v28, v48, v49
	v_cvt_pk_bf16_f32 v29, v46, v47
	v_cvt_pk_bf16_f32 v30, v30, v31
	v_cvt_pk_bf16_f32 v31, v34, v35
	v_lshl_add_u64 v[32:33], v[32:33], 0, v[60:61]
	v_lshl_add_u64 v[36:37], v[72:73], 0, s[0:1]
	global_store_dwordx4 v[32:33], v[28:31], off
	v_lshl_add_u64 v[32:33], v[68:69], 0, v[36:37]
	s_nop 0
	v_lshl_add_u64 v[28:29], v[70:71], 0, v[36:37]
	s_nop 0
	s_mov_b64 s[0:1], 0x5000
	s_waitcnt vmcnt(10)
	v_pk_mul_f32 v[38:39], v[22:23], v[174:175]
	v_pk_mul_f32 v[40:41], v[20:21], v[172:173]
	s_waitcnt vmcnt(9)
	v_pk_fma_f32 v[38:39], v[26:27], v[120:121], v[38:39] neg_lo:[0,0,1] neg_hi:[0,0,1]
	v_pk_fma_f32 v[40:41], v[24:25], v[118:119], v[40:41] neg_lo:[0,0,1] neg_hi:[0,0,1]
	v_pk_mul_f32 v[26:27], v[26:27], v[174:175]
	v_pk_mul_f32 v[24:25], v[24:25], v[172:173]
	v_pk_fma_f32 v[26:27], v[22:23], v[120:121], v[26:27]
	v_pk_fma_f32 v[22:23], v[20:21], v[118:119], v[24:25]
	v_lshl_add_u64 v[24:25], s[28:29], 0, v[36:37]
	v_cvt_pk_bf16_f32 v20, v40, v41
	v_cvt_pk_bf16_f32 v21, v38, v39
	v_cvt_pk_bf16_f32 v22, v22, v23
	v_cvt_pk_bf16_f32 v23, v26, v27
	v_lshl_add_u64 v[24:25], v[24:25], 0, v[60:61]
	v_lshl_add_u64 v[28:29], v[72:73], 0, s[0:1]
	global_store_dwordx4 v[24:25], v[20:23], off
	v_lshl_add_u64 v[24:25], v[68:69], 0, v[28:29]
	s_nop 0
	v_lshl_add_u64 v[20:21], v[70:71], 0, v[28:29]
	s_nop 0
	s_mov_b64 s[0:1], 0x5800
	s_waitcnt vmcnt(9)
	v_pk_mul_f32 v[30:31], v[14:15], v[178:179]
	v_pk_mul_f32 v[32:33], v[12:13], v[176:177]
	s_waitcnt vmcnt(8)
	v_pk_fma_f32 v[30:31], v[18:19], v[124:125], v[30:31] neg_lo:[0,0,1] neg_hi:[0,0,1]
	v_pk_fma_f32 v[32:33], v[16:17], v[122:123], v[32:33] neg_lo:[0,0,1] neg_hi:[0,0,1]
	v_pk_mul_f32 v[18:19], v[18:19], v[178:179]
	v_pk_mul_f32 v[16:17], v[16:17], v[176:177]
	v_pk_fma_f32 v[18:19], v[14:15], v[124:125], v[18:19]
	v_pk_fma_f32 v[14:15], v[12:13], v[122:123], v[16:17]
	v_lshl_add_u64 v[16:17], s[28:29], 0, v[28:29]
	v_cvt_pk_bf16_f32 v12, v32, v33
	v_cvt_pk_bf16_f32 v13, v30, v31
	v_cvt_pk_bf16_f32 v14, v14, v15
	v_cvt_pk_bf16_f32 v15, v18, v19
	v_lshl_add_u64 v[16:17], v[16:17], 0, v[60:61]
	v_lshl_add_u64 v[20:21], v[72:73], 0, s[0:1]
	global_store_dwordx4 v[16:17], v[12:15], off
	v_lshl_add_u64 v[16:17], v[68:69], 0, v[20:21]
	s_nop 0
	v_lshl_add_u64 v[12:13], v[70:71], 0, v[20:21]
	s_nop 0
	s_waitcnt vmcnt(8)
	v_pk_mul_f32 v[22:23], v[6:7], v[182:183]
	v_pk_mul_f32 v[24:25], v[4:5], v[180:181]
	s_waitcnt vmcnt(7)
	v_pk_fma_f32 v[22:23], v[10:11], v[128:129], v[22:23] neg_lo:[0,0,1] neg_hi:[0,0,1]
	v_pk_fma_f32 v[24:25], v[8:9], v[126:127], v[24:25] neg_lo:[0,0,1] neg_hi:[0,0,1]
	v_pk_mul_f32 v[10:11], v[10:11], v[182:183]
	v_pk_mul_f32 v[8:9], v[8:9], v[180:181]
	v_pk_fma_f32 v[10:11], v[6:7], v[128:129], v[10:11]
	v_pk_fma_f32 v[6:7], v[4:5], v[126:127], v[8:9]
	v_lshl_add_u64 v[8:9], s[28:29], 0, v[20:21]
	v_cvt_pk_bf16_f32 v4, v24, v25
	v_cvt_pk_bf16_f32 v5, v22, v23
	v_cvt_pk_bf16_f32 v6, v6, v7
	v_cvt_pk_bf16_f32 v7, v10, v11
	v_lshl_add_u64 v[8:9], v[8:9], 0, v[60:61]
	global_store_dwordx4 v[8:9], v[4:7], off
